# sc1 write-through also for the layer-0 weight conversion in the prologue (same reasoning as the per-layer conversion)
# speedup vs baseline: 1.0173x; 1.0173x over previous
; #define LAS __attribute__((address_space(3)))
; __device__ __forceinline__ void wconv_item(const float* W, int K, int Norig, int Nphys, bf16_t* WT, const float* gA, const float* gB, int split, int mapid, LAS float* scr, int item, int lane) {
;     const int nblk = Nphys / 32, kb = item / nblk, nb = item % nblk, k0 = 64 * kb, n0 = 32 * nb;
;     const int norig = colmap(mapid, n0 + (lane & 31));
;     float wv[32];
; #pragma unroll
;     for (int i = 0; i < 32; ++i) { const int k = k0 + 2 * i + (lane >> 5); wv[i] = (norig >= 0) ? W[(size_t)k * Norig + norig] : 0.f; }
; template <class AP> __device__ __forceinline__ void convert_weights(AP a, int L, bf16_t* wb, LAS float* scr, int gw, int NGW, int lane) {
;     ...
;     for (int it = gw; it < NIT; it += NGW) {
;         int r = it;
;         if (r < I0) { wconv_item(w_in, 1024, INC, INP, wb + WO_IN, g_mix, g_mix, 1024, 0, scr, r, lane); continue; } r -= I0;
;         if (r < I1) { wconv_item(w_uq, QL, 768, 768, wb + WO_UQ, g_ql, g_ql, QL, 1, scr, r, lane); continue; } r -= I1;
;         if (r < I2) { wconv_item(w_ukv, KVL, 1024, 1024, wb + WO_UKV, g_kvl, g_kvl, KVL, 2, scr, r, lane); continue; } r -= I2;
;         if (r < I3) { wconv_item(w_o, 1024, 1024, 1024, wb + WO_O, g_oa, g_oc, 512, 3, scr, r, lane); continue; } r -= I3;
;         if (r < I4) { wconv_item(w_up, 1024, FF, FF, wb + WO_UP, g_mlp, g_mlp, 1024, 3, scr, r, lane); continue; } r -= I4;
;         if (r < I5) { wconv_item(w_dn, FF, 1024, 1024, wb + WO_DN, nullptr, nullptr, 0, 3, scr, r, lane); continue; } r -= I5;
;         if (r < I6) { wconv_item(w_g, 1024, 1024, 1024, wb + WO_G, g_ple, g_ple, 1024, 3, scr, r, lane); continue; } r -= I6;
;         wconv_item(w_ple, PLE, 1024, 1024, wb + WO_PLE, nullptr, nullptr, 0, 3, scr, r, lane);
.LBB0_12:
	s_cmpk_gt_i32 s74, 0x47f
	s_mov_b64 s[4:5], -1
	s_cbranch_scc0 .LBB0_106
	s_cmpk_gt_u32 s74, 0x50f
	s_cbranch_scc0 .LBB0_87
	s_cmpk_gt_u32 s74, 0x58f
	s_cbranch_scc0 .LBB0_68
	s_cmpk_gt_u32 s74, 0x78f
	s_cbranch_scc0 .LBB0_53
	s_cmpk_gt_u32 s74, 0xf8f
	s_cbranch_scc0 .LBB0_38
	s_cmpk_gt_u32 s74, 0x178f
	s_cbranch_scc0 .LBB0_35
	s_cmpk_gt_u32 s74, 0x198f
	s_cbranch_scc0 .LBB0_20
	s_add_i32 s4, s87, 0xfffcce00
	s_and_b32 s4, s4, 0x3e0
	s_and_b32 s5, s89, 0x1c0
	v_or_b32_e32 v4, s4, v1
	v_or_b32_e32 v24, s5, v2
	v_lshlrev_b32_e32 v4, 2, v4
	v_lshl_add_u64 v[22:23], s[6:7], 0, v[4:5]
	v_lshlrev_b32_e32 v4, 12, v24
	v_lshl_add_u64 v[22:23], v[22:23], 0, v[4:5]
	v_add_co_u32_e32 v24, vcc, 0x2000, v22
	s_lshl_b32 s34, s5, 1
	s_nop 0
	v_addc_co_u32_e32 v25, vcc, 0, v23, vcc
	v_add_co_u32_e32 v26, vcc, 0x4000, v22
	s_nop 1
	v_addc_co_u32_e32 v27, vcc, 0, v23, vcc
	v_add_co_u32_e32 v28, vcc, 0x6000, v22
	s_nop 1
	v_addc_co_u32_e32 v29, vcc, 0, v23, vcc
	v_add_co_u32_e32 v30, vcc, 0x8000, v22
	s_nop 1
	v_addc_co_u32_e32 v31, vcc, 0, v23, vcc
	v_add_co_u32_e32 v32, vcc, 0xa000, v22
	s_nop 1
	v_addc_co_u32_e32 v33, vcc, 0, v23, vcc
	v_add_co_u32_e32 v34, vcc, 0xc000, v22
	s_nop 1
	v_addc_co_u32_e32 v35, vcc, 0, v23, vcc
	v_add_co_u32_e32 v36, vcc, 0xe000, v22
	s_nop 1
	v_addc_co_u32_e32 v37, vcc, 0, v23, vcc
	global_load_dword v4, v[22:23], off nt
	global_load_dword v40, v[24:25], off nt
	global_load_dword v41, v[26:27], off nt
	global_load_dword v42, v[28:29], off nt
	global_load_dword v43, v[30:31], off nt
	global_load_dword v93, v[32:33], off nt
	global_load_dword v94, v[34:35], off nt
	global_load_dword v95, v[36:37], off nt
	v_add_co_u32_e32 v24, vcc, 0x10000, v22
	s_nop 1
	v_addc_co_u32_e32 v25, vcc, 0, v23, vcc
	v_add_co_u32_e32 v26, vcc, 0x12000, v22
	s_nop 1
	v_addc_co_u32_e32 v27, vcc, 0, v23, vcc
	v_add_co_u32_e32 v28, vcc, 0x14000, v22
	s_nop 1
	v_addc_co_u32_e32 v29, vcc, 0, v23, vcc
	v_add_co_u32_e32 v30, vcc, 0x16000, v22
	s_nop 1
	v_addc_co_u32_e32 v31, vcc, 0, v23, vcc
	v_add_co_u32_e32 v32, vcc, 0x18000, v22
	s_nop 1
	v_addc_co_u32_e32 v33, vcc, 0, v23, vcc
	v_add_co_u32_e32 v34, vcc, 0x1a000, v22
	s_nop 1
	v_addc_co_u32_e32 v35, vcc, 0, v23, vcc
	v_add_co_u32_e32 v36, vcc, 0x1c000, v22
	s_nop 1
	v_addc_co_u32_e32 v37, vcc, 0, v23, vcc
	v_add_co_u32_e32 v38, vcc, 0x1e000, v22
	s_nop 1
	v_addc_co_u32_e32 v39, vcc, 0, v23, vcc
	global_load_dword v96, v[24:25], off nt
	global_load_dword v97, v[26:27], off nt
	global_load_dword v98, v[28:29], off nt
	global_load_dword v99, v[30:31], off nt
	global_load_dword v100, v[32:33], off nt
	global_load_dword v101, v[34:35], off nt
	global_load_dword v102, v[36:37], off nt
	global_load_dword v103, v[38:39], off nt
	v_add_co_u32_e32 v24, vcc, 0x20000, v22
	s_nop 1
	v_addc_co_u32_e32 v25, vcc, 0, v23, vcc
	v_add_co_u32_e32 v26, vcc, 0x22000, v22
	s_nop 1
	v_addc_co_u32_e32 v27, vcc, 0, v23, vcc
	v_add_co_u32_e32 v28, vcc, 0x24000, v22
	s_nop 1
	v_addc_co_u32_e32 v29, vcc, 0, v23, vcc
	v_add_co_u32_e32 v30, vcc, 0x26000, v22
	s_nop 1
	v_addc_co_u32_e32 v31, vcc, 0, v23, vcc
	v_add_co_u32_e32 v32, vcc, 0x28000, v22
	s_nop 1
	v_addc_co_u32_e32 v33, vcc, 0, v23, vcc
	v_add_co_u32_e32 v34, vcc, 0x2a000, v22
	s_nop 1
	v_addc_co_u32_e32 v35, vcc, 0, v23, vcc
	v_add_co_u32_e32 v36, vcc, 0x2c000, v22
	s_nop 1
	v_addc_co_u32_e32 v37, vcc, 0, v23, vcc
	v_add_co_u32_e32 v38, vcc, 0x2e000, v22
	s_nop 1
	v_addc_co_u32_e32 v39, vcc, 0, v23, vcc
	global_load_dword v104, v[24:25], off nt
	global_load_dword v105, v[26:27], off nt
	global_load_dword v106, v[28:29], off nt
	global_load_dword v107, v[30:31], off nt
	global_load_dword v108, v[32:33], off nt
	global_load_dword v109, v[34:35], off nt
	global_load_dword v110, v[36:37], off nt
	s_nop 0
	global_load_dword v38, v[38:39], off nt
	v_add_co_u32_e32 v24, vcc, 0x30000, v22
	s_nop 1
	v_addc_co_u32_e32 v25, vcc, 0, v23, vcc
	v_add_co_u32_e32 v26, vcc, 0x32000, v22
	s_nop 1
	v_addc_co_u32_e32 v27, vcc, 0, v23, vcc
	v_add_co_u32_e32 v28, vcc, 0x34000, v22
	s_nop 1
	v_addc_co_u32_e32 v29, vcc, 0, v23, vcc
	v_add_co_u32_e32 v30, vcc, 0x36000, v22
	s_nop 1
	v_addc_co_u32_e32 v31, vcc, 0, v23, vcc
	v_add_co_u32_e32 v32, vcc, 0x38000, v22
	s_nop 1
	v_addc_co_u32_e32 v33, vcc, 0, v23, vcc
	v_add_co_u32_e32 v34, vcc, 0x3a000, v22
	s_nop 1
	v_addc_co_u32_e32 v35, vcc, 0, v23, vcc
	v_add_co_u32_e32 v36, vcc, 0x3c000, v22
	s_nop 1
	v_addc_co_u32_e32 v37, vcc, 0, v23, vcc
	v_add_co_u32_e32 v22, vcc, 0x3e000, v22
	s_nop 1
	v_addc_co_u32_e32 v23, vcc, 0, v23, vcc
	global_load_dword v24, v[24:25], off nt
	s_nop 0
	global_load_dword v25, v[26:27], off nt
	s_nop 0
	global_load_dword v26, v[28:29], off nt
	global_load_dword v27, v[30:31], off nt
	s_nop 0
	global_load_dword v28, v[32:33], off nt
	global_load_dword v29, v[34:35], off nt
	global_load_dword v30, v[36:37], off nt
	s_nop 0
	global_load_dword v22, v[22:23], off nt
	s_waitcnt vmcnt(30)
; #define LAS __attribute__((address_space(3)))
; __device__ __forceinline__ unsigned cvt_pk_bf16(float lo, float hi) { unsigned r; asm volatile("v_cvt_pk_bf16_f32 %0, %1, %2" : "=v"(r) : "v"(lo), "v"(hi)); return r; }
; __device__ __forceinline__ void wconv_item(const float* W, int K, int Norig, int Nphys, bf16_t* WT, const float* gA, const float* gB, int split, int mapid, LAS float* scr, int item, int lane) {
;     ...
; #pragma unroll
;     for (int i = 0; i < 32; ++i) { const int kk = 2 * i + (lane >> 5), k = k0 + kk;
;         float v = wv[i];
;         if (gA) v *= (k < split ? gA[k] : gB[k - split]);
;         scr[kk * 33 + (lane & 31)] = v; }
;     asm volatile("s_waitcnt lgkmcnt(0)" ::: "memory");
;     const int c = lane & 7;
; #pragma unroll
;     for (int j = 0; j < 4; ++j) { const int n = (lane >> 3) + 8 * j; const LAS float* s = scr + (8 * c) * 33 + n;
;         u32x4 o; o.x = cvt_pk_bf16(s[0 * 33], s[1 * 33]); o.y = cvt_pk_bf16(s[2 * 33], s[3 * 33]); o.z = cvt_pk_bf16(s[4 * 33], s[5 * 33]); o.w = cvt_pk_bf16(s[6 * 33], s[7 * 33]);
;         *(u32x4*)(WT + (size_t)(n0 + n) * K + k0 + 8 * c) = o; }
;     asm volatile("s_waitcnt lgkmcnt(0)" ::: "memory");
	ds_write2_b32 v45, v4, v40 offset1:66
	s_waitcnt vmcnt(28)
	ds_write2_b32 v45, v41, v42 offset0:132 offset1:198
	v_add_u32_e32 v4, 0x400, v45
	s_waitcnt vmcnt(26)
	ds_write2_b32 v4, v43, v93 offset0:8 offset1:74
	s_waitcnt vmcnt(24)
	ds_write2_b32 v4, v94, v95 offset0:140 offset1:206
	v_add_u32_e32 v4, 0x800, v45
	s_waitcnt vmcnt(22)
	ds_write2_b32 v4, v96, v97 offset0:16 offset1:82
	s_waitcnt vmcnt(20)
	ds_write2_b32 v4, v98, v99 offset0:148 offset1:214
	v_add_u32_e32 v4, 0xc00, v45
	s_waitcnt vmcnt(18)
	ds_write2_b32 v4, v100, v101 offset0:24 offset1:90
	s_waitcnt vmcnt(16)
	ds_write2_b32 v4, v102, v103 offset0:156 offset1:222
	v_add_u32_e32 v4, 0x1000, v45
	s_waitcnt vmcnt(14)
	ds_write2_b32 v4, v104, v105 offset0:32 offset1:98
	s_waitcnt vmcnt(12)
	ds_write2_b32 v4, v106, v107 offset0:164 offset1:230
	v_add_u32_e32 v4, 0x1400, v45
	s_waitcnt vmcnt(10)
	ds_write2_b32 v4, v108, v109 offset0:40 offset1:106
	s_waitcnt vmcnt(8)
	ds_write2_b32 v4, v110, v38 offset0:172 offset1:238
	v_add_u32_e32 v4, 0x1800, v45
	s_waitcnt vmcnt(6)
	ds_write2_b32 v4, v24, v25 offset0:48 offset1:114
	s_waitcnt vmcnt(4)
	ds_write2_b32 v4, v26, v27 offset0:180 offset1:246
	v_add_u32_e32 v4, 0x1c00, v45
	s_waitcnt vmcnt(2)
	ds_write2_b32 v4, v28, v29 offset0:56 offset1:122
	s_waitcnt vmcnt(0)
	ds_write2_b32 v4, v30, v22 offset0:188 offset1:254
	s_waitcnt lgkmcnt(0)
	ds_read2_b32 v[22:23], v47 offset1:33
	s_waitcnt lgkmcnt(0)
	v_cvt_pk_bf16_f32 v22, v22, v23
	ds_read2_b32 v[24:25], v47 offset0:66 offset1:99
	v_or_b32_e32 v4, s4, v46
	s_waitcnt lgkmcnt(0)
	v_cvt_pk_bf16_f32 v23, v24, v25
	ds_read2_b32 v[24:25], v47 offset0:132 offset1:165
	v_lshl_add_u64 v[28:29], v[6:7], 0, s[34:35]
	v_lshlrev_b32_e32 v4, 9, v4
	s_waitcnt lgkmcnt(0)
	v_cvt_pk_bf16_f32 v24, v24, v25
	ds_read2_b32 v[26:27], v47 offset0:198 offset1:231
	s_waitcnt lgkmcnt(0)
	v_cvt_pk_bf16_f32 v25, v26, v27
	v_lshl_add_u64 v[30:31], v[28:29], 0, v[4:5]
	ds_read2_b32 v[26:27], v47 offset0:8 offset1:41
	global_store_dwordx4 v[30:31], v[22:25], off sc1
	v_or_b32_e32 v4, s4, v48
	v_lshlrev_b32_e32 v4, 9, v4
	s_waitcnt lgkmcnt(0)
	v_cvt_pk_bf16_f32 v22, v26, v27
	ds_read2_b32 v[24:25], v47 offset0:74 offset1:107
	s_waitcnt lgkmcnt(0)
	v_cvt_pk_bf16_f32 v23, v24, v25
	ds_read2_b32 v[24:25], v47 offset0:140 offset1:173
	s_waitcnt lgkmcnt(0)
	v_cvt_pk_bf16_f32 v24, v24, v25
	ds_read2_b32 v[26:27], v47 offset0:206 offset1:239
	s_waitcnt lgkmcnt(0)
	v_cvt_pk_bf16_f32 v25, v26, v27
	v_lshl_add_u64 v[30:31], v[28:29], 0, v[4:5]
	ds_read2_b32 v[26:27], v47 offset0:16 offset1:49
	global_store_dwordx4 v[30:31], v[22:25], off sc1
	v_or_b32_e32 v4, s4, v49
	v_lshlrev_b32_e32 v4, 9, v4
	s_waitcnt lgkmcnt(0)
	v_cvt_pk_bf16_f32 v22, v26, v27
	ds_read2_b32 v[24:25], v47 offset0:82 offset1:115
	s_waitcnt lgkmcnt(0)
	v_cvt_pk_bf16_f32 v23, v24, v25
	ds_read2_b32 v[24:25], v47 offset0:148 offset1:181
	s_waitcnt lgkmcnt(0)
	v_cvt_pk_bf16_f32 v24, v24, v25
	ds_read2_b32 v[26:27], v47 offset0:214 offset1:247
	s_waitcnt lgkmcnt(0)
	v_cvt_pk_bf16_f32 v25, v26, v27
	v_lshl_add_u64 v[30:31], v[28:29], 0, v[4:5]
	ds_read2_b32 v[26:27], v47 offset0:24 offset1:57
	global_store_dwordx4 v[30:31], v[22:25], off sc1
	v_or_b32_e32 v4, s4, v50
	v_lshlrev_b32_e32 v4, 9, v4
	s_waitcnt lgkmcnt(0)
	v_cvt_pk_bf16_f32 v22, v26, v27
	ds_read2_b32 v[24:25], v47 offset0:90 offset1:123
	s_waitcnt lgkmcnt(0)
	v_cvt_pk_bf16_f32 v23, v24, v25
	ds_read2_b32 v[24:25], v47 offset0:156 offset1:189
	s_waitcnt lgkmcnt(0)
	v_cvt_pk_bf16_f32 v24, v24, v25
	ds_read2_b32 v[26:27], v47 offset0:222 offset1:255
	s_waitcnt lgkmcnt(0)
	v_cvt_pk_bf16_f32 v25, v26, v27
	v_lshl_add_u64 v[26:27], v[28:29], 0, v[4:5]
	global_store_dwordx4 v[26:27], v[22:25], off sc1
	s_waitcnt lgkmcnt(0)
	s_mov_b64 s[4:5], 0

; #define LAS __attribute__((address_space(3)))
; __device__ __forceinline__ void wconv_item(const float* W, int K, int Norig, int Nphys, bf16_t* WT, const float* gA, const float* gB, int split, int mapid, LAS float* scr, int item, int lane) {
;     const int nblk = Nphys / 32, kb = item / nblk, nb = item % nblk, k0 = 64 * kb, n0 = 32 * nb;
;     const int norig = colmap(mapid, n0 + (lane & 31));
;     float wv[32];
; #pragma unroll
;     for (int i = 0; i < 32; ++i) { const int k = k0 + 2 * i + (lane >> 5); wv[i] = (norig >= 0) ? W[(size_t)k * Norig + norig] : 0.f; }
; template <class AP> __device__ __forceinline__ void convert_weights(AP a, int L, bf16_t* wb, LAS float* scr, int gw, int NGW, int lane) {
;     ...
;         if (r < I5) { wconv_item(w_dn, FF, 1024, 1024, wb + WO_DN, nullptr, nullptr, 0, 3, scr, r, lane); continue; } r -= I5;
.LBB0_35:
	s_andn2_b64 vcc, exec, s[4:5]
	s_cbranch_vccnz .LBB0_37
	s_add_i32 s4, s89, 0x1400
	s_and_b32 s5, s4, 0x1ffc0
	s_add_i32 s4, s87, 0xfffe0e00
	s_and_b32 s4, s4, 0x3e0
	v_or_b32_e32 v4, s4, v1
	v_or_b32_e32 v24, s5, v2
	v_lshlrev_b32_e32 v4, 2, v4
	v_lshl_add_u64 v[22:23], s[18:19], 0, v[4:5]
	v_lshlrev_b32_e32 v4, 12, v24
	v_lshl_add_u64 v[22:23], v[22:23], 0, v[4:5]
	v_add_co_u32_e32 v24, vcc, 0x2000, v22
	s_lshl_b32 s34, s5, 1
	s_nop 0
	v_addc_co_u32_e32 v25, vcc, 0, v23, vcc
	v_add_co_u32_e32 v26, vcc, 0x4000, v22
	s_nop 1
	v_addc_co_u32_e32 v27, vcc, 0, v23, vcc
	v_add_co_u32_e32 v28, vcc, 0x6000, v22
	s_nop 1
	v_addc_co_u32_e32 v29, vcc, 0, v23, vcc
	v_add_co_u32_e32 v30, vcc, 0x8000, v22
	s_nop 1
	v_addc_co_u32_e32 v31, vcc, 0, v23, vcc
	v_add_co_u32_e32 v32, vcc, 0xa000, v22
	s_nop 1
	v_addc_co_u32_e32 v33, vcc, 0, v23, vcc
	v_add_co_u32_e32 v34, vcc, 0xc000, v22
	s_nop 1
	v_addc_co_u32_e32 v35, vcc, 0, v23, vcc
	v_add_co_u32_e32 v36, vcc, 0xe000, v22
	s_nop 1
	v_addc_co_u32_e32 v37, vcc, 0, v23, vcc
	global_load_dword v4, v[22:23], off nt
	global_load_dword v40, v[24:25], off nt
	global_load_dword v41, v[26:27], off nt
	global_load_dword v42, v[28:29], off nt
	global_load_dword v43, v[30:31], off nt
	global_load_dword v93, v[32:33], off nt
	global_load_dword v94, v[34:35], off nt
	global_load_dword v95, v[36:37], off nt
	v_add_co_u32_e32 v24, vcc, 0x10000, v22
	s_nop 1
	v_addc_co_u32_e32 v25, vcc, 0, v23, vcc
	v_add_co_u32_e32 v26, vcc, 0x12000, v22
	s_nop 1
	v_addc_co_u32_e32 v27, vcc, 0, v23, vcc
	v_add_co_u32_e32 v28, vcc, 0x14000, v22
	s_nop 1
	v_addc_co_u32_e32 v29, vcc, 0, v23, vcc
	v_add_co_u32_e32 v30, vcc, 0x16000, v22
	s_nop 1
	v_addc_co_u32_e32 v31, vcc, 0, v23, vcc
	v_add_co_u32_e32 v32, vcc, 0x18000, v22
	s_nop 1
	v_addc_co_u32_e32 v33, vcc, 0, v23, vcc
	v_add_co_u32_e32 v34, vcc, 0x1a000, v22
	s_nop 1
	v_addc_co_u32_e32 v35, vcc, 0, v23, vcc
	v_add_co_u32_e32 v36, vcc, 0x1c000, v22
	s_nop 1
	v_addc_co_u32_e32 v37, vcc, 0, v23, vcc
	v_add_co_u32_e32 v38, vcc, 0x1e000, v22
	s_nop 1
	v_addc_co_u32_e32 v39, vcc, 0, v23, vcc
	global_load_dword v96, v[24:25], off nt
	global_load_dword v97, v[26:27], off nt
	global_load_dword v98, v[28:29], off nt
	global_load_dword v99, v[30:31], off nt
	global_load_dword v100, v[32:33], off nt
	global_load_dword v101, v[34:35], off nt
	global_load_dword v102, v[36:37], off nt
	global_load_dword v103, v[38:39], off nt
	v_add_co_u32_e32 v24, vcc, 0x20000, v22
	s_nop 1
	v_addc_co_u32_e32 v25, vcc, 0, v23, vcc
	v_add_co_u32_e32 v26, vcc, 0x22000, v22
	s_nop 1
	v_addc_co_u32_e32 v27, vcc, 0, v23, vcc
	v_add_co_u32_e32 v28, vcc, 0x24000, v22
	s_nop 1
	v_addc_co_u32_e32 v29, vcc, 0, v23, vcc
	v_add_co_u32_e32 v30, vcc, 0x26000, v22
	s_nop 1
	v_addc_co_u32_e32 v31, vcc, 0, v23, vcc
	v_add_co_u32_e32 v32, vcc, 0x28000, v22
	s_nop 1
	v_addc_co_u32_e32 v33, vcc, 0, v23, vcc
	v_add_co_u32_e32 v34, vcc, 0x2a000, v22
	s_nop 1
	v_addc_co_u32_e32 v35, vcc, 0, v23, vcc
	v_add_co_u32_e32 v36, vcc, 0x2c000, v22
	s_nop 1
	v_addc_co_u32_e32 v37, vcc, 0, v23, vcc
	v_add_co_u32_e32 v38, vcc, 0x2e000, v22
	s_nop 1
	v_addc_co_u32_e32 v39, vcc, 0, v23, vcc
	global_load_dword v104, v[24:25], off nt
	global_load_dword v105, v[26:27], off nt
	global_load_dword v106, v[28:29], off nt
	global_load_dword v107, v[30:31], off nt
	global_load_dword v108, v[32:33], off nt
	global_load_dword v109, v[34:35], off nt
	global_load_dword v110, v[36:37], off nt
	s_nop 0
	global_load_dword v38, v[38:39], off nt
	v_add_co_u32_e32 v24, vcc, 0x30000, v22
	s_nop 1
	v_addc_co_u32_e32 v25, vcc, 0, v23, vcc
	v_add_co_u32_e32 v26, vcc, 0x32000, v22
	s_nop 1
	v_addc_co_u32_e32 v27, vcc, 0, v23, vcc
	v_add_co_u32_e32 v28, vcc, 0x34000, v22
	s_nop 1
	v_addc_co_u32_e32 v29, vcc, 0, v23, vcc
	v_add_co_u32_e32 v30, vcc, 0x36000, v22
	s_nop 1
	v_addc_co_u32_e32 v31, vcc, 0, v23, vcc
	v_add_co_u32_e32 v32, vcc, 0x38000, v22
	s_nop 1
	v_addc_co_u32_e32 v33, vcc, 0, v23, vcc
	v_add_co_u32_e32 v34, vcc, 0x3a000, v22
	s_nop 1
	v_addc_co_u32_e32 v35, vcc, 0, v23, vcc
	v_add_co_u32_e32 v36, vcc, 0x3c000, v22
	s_nop 1
	v_addc_co_u32_e32 v37, vcc, 0, v23, vcc
	v_add_co_u32_e32 v22, vcc, 0x3e000, v22
	s_nop 1
	v_addc_co_u32_e32 v23, vcc, 0, v23, vcc
	global_load_dword v24, v[24:25], off nt
	s_nop 0
	global_load_dword v25, v[26:27], off nt
	s_nop 0
	global_load_dword v26, v[28:29], off nt
	global_load_dword v27, v[30:31], off nt
	s_nop 0
	global_load_dword v28, v[32:33], off nt
	global_load_dword v29, v[34:35], off nt
	global_load_dword v30, v[36:37], off nt
	s_nop 0
	global_load_dword v22, v[22:23], off nt
	s_waitcnt vmcnt(30)
; #define LAS __attribute__((address_space(3)))
; __device__ __forceinline__ unsigned cvt_pk_bf16(float lo, float hi) { unsigned r; asm volatile("v_cvt_pk_bf16_f32 %0, %1, %2" : "=v"(r) : "v"(lo), "v"(hi)); return r; }
; __device__ __forceinline__ void wconv_item(const float* W, int K, int Norig, int Nphys, bf16_t* WT, const float* gA, const float* gB, int split, int mapid, LAS float* scr, int item, int lane) {
;     ...
; #pragma unroll
;     for (int i = 0; i < 32; ++i) { const int kk = 2 * i + (lane >> 5), k = k0 + kk;
;         float v = wv[i];
;         if (gA) v *= (k < split ? gA[k] : gB[k - split]);
;         scr[kk * 33 + (lane & 31)] = v; }
;     asm volatile("s_waitcnt lgkmcnt(0)" ::: "memory");
;     const int c = lane & 7;
; #pragma unroll
;     for (int j = 0; j < 4; ++j) { const int n = (lane >> 3) + 8 * j; const LAS float* s = scr + (8 * c) * 33 + n;
;         u32x4 o; o.x = cvt_pk_bf16(s[0 * 33], s[1 * 33]); o.y = cvt_pk_bf16(s[2 * 33], s[3 * 33]); o.z = cvt_pk_bf16(s[4 * 33], s[5 * 33]); o.w = cvt_pk_bf16(s[6 * 33], s[7 * 33]);
;         *(u32x4*)(WT + (size_t)(n0 + n) * K + k0 + 8 * c) = o; }
;     asm volatile("s_waitcnt lgkmcnt(0)" ::: "memory");
	ds_write2_b32 v45, v4, v40 offset1:66
	s_waitcnt vmcnt(28)
	ds_write2_b32 v45, v41, v42 offset0:132 offset1:198
	v_add_u32_e32 v4, 0x400, v45
	s_waitcnt vmcnt(26)
	ds_write2_b32 v4, v43, v93 offset0:8 offset1:74
	s_waitcnt vmcnt(24)
	ds_write2_b32 v4, v94, v95 offset0:140 offset1:206
	v_add_u32_e32 v4, 0x800, v45
	s_waitcnt vmcnt(22)
	ds_write2_b32 v4, v96, v97 offset0:16 offset1:82
	s_waitcnt vmcnt(20)
	ds_write2_b32 v4, v98, v99 offset0:148 offset1:214
	v_add_u32_e32 v4, 0xc00, v45
	s_waitcnt vmcnt(18)
	ds_write2_b32 v4, v100, v101 offset0:24 offset1:90
	s_waitcnt vmcnt(16)
	ds_write2_b32 v4, v102, v103 offset0:156 offset1:222
	v_add_u32_e32 v4, 0x1000, v45
	s_waitcnt vmcnt(14)
	ds_write2_b32 v4, v104, v105 offset0:32 offset1:98
	s_waitcnt vmcnt(12)
	ds_write2_b32 v4, v106, v107 offset0:164 offset1:230
	v_add_u32_e32 v4, 0x1400, v45
	s_waitcnt vmcnt(10)
	ds_write2_b32 v4, v108, v109 offset0:40 offset1:106
	s_waitcnt vmcnt(8)
	ds_write2_b32 v4, v110, v38 offset0:172 offset1:238
	v_add_u32_e32 v4, 0x1800, v45
	s_waitcnt vmcnt(6)
	ds_write2_b32 v4, v24, v25 offset0:48 offset1:114
	s_waitcnt vmcnt(4)
	ds_write2_b32 v4, v26, v27 offset0:180 offset1:246
	v_add_u32_e32 v4, 0x1c00, v45
	s_waitcnt vmcnt(2)
	ds_write2_b32 v4, v28, v29 offset0:56 offset1:122
	s_waitcnt vmcnt(0)
	ds_write2_b32 v4, v30, v22 offset0:188 offset1:254
	s_waitcnt lgkmcnt(0)
	ds_read2_b32 v[22:23], v47 offset1:33
	s_waitcnt lgkmcnt(0)
	v_cvt_pk_bf16_f32 v22, v22, v23
	ds_read2_b32 v[24:25], v47 offset0:66 offset1:99
	v_or_b32_e32 v4, s4, v46
	s_waitcnt lgkmcnt(0)
	v_cvt_pk_bf16_f32 v23, v24, v25
	ds_read2_b32 v[24:25], v47 offset0:132 offset1:165
	v_lshl_add_u64 v[28:29], v[10:11], 0, s[34:35]
	v_lshlrev_b32_e32 v4, 13, v4
	s_waitcnt lgkmcnt(0)
	v_cvt_pk_bf16_f32 v24, v24, v25
	ds_read2_b32 v[26:27], v47 offset0:198 offset1:231
	s_waitcnt lgkmcnt(0)
	v_cvt_pk_bf16_f32 v25, v26, v27
	v_lshl_add_u64 v[30:31], v[28:29], 0, v[4:5]
	ds_read2_b32 v[26:27], v47 offset0:8 offset1:41
	global_store_dwordx4 v[30:31], v[22:25], off sc1
	v_or_b32_e32 v4, s4, v48
	v_lshlrev_b32_e32 v4, 13, v4
	s_waitcnt lgkmcnt(0)
	v_cvt_pk_bf16_f32 v22, v26, v27
	ds_read2_b32 v[24:25], v47 offset0:74 offset1:107
	s_waitcnt lgkmcnt(0)
	v_cvt_pk_bf16_f32 v23, v24, v25
	ds_read2_b32 v[24:25], v47 offset0:140 offset1:173
	s_waitcnt lgkmcnt(0)
	v_cvt_pk_bf16_f32 v24, v24, v25
	ds_read2_b32 v[26:27], v47 offset0:206 offset1:239
	s_waitcnt lgkmcnt(0)
	v_cvt_pk_bf16_f32 v25, v26, v27
	v_lshl_add_u64 v[30:31], v[28:29], 0, v[4:5]
	ds_read2_b32 v[26:27], v47 offset0:16 offset1:49
	global_store_dwordx4 v[30:31], v[22:25], off sc1
	v_or_b32_e32 v4, s4, v49
	v_lshlrev_b32_e32 v4, 13, v4
	s_waitcnt lgkmcnt(0)
	v_cvt_pk_bf16_f32 v22, v26, v27
	ds_read2_b32 v[24:25], v47 offset0:82 offset1:115
	s_waitcnt lgkmcnt(0)
	v_cvt_pk_bf16_f32 v23, v24, v25
	ds_read2_b32 v[24:25], v47 offset0:148 offset1:181
	s_waitcnt lgkmcnt(0)
	v_cvt_pk_bf16_f32 v24, v24, v25
	ds_read2_b32 v[26:27], v47 offset0:214 offset1:247
	s_waitcnt lgkmcnt(0)
	v_cvt_pk_bf16_f32 v25, v26, v27
	v_lshl_add_u64 v[30:31], v[28:29], 0, v[4:5]
	ds_read2_b32 v[26:27], v47 offset0:24 offset1:57
	global_store_dwordx4 v[30:31], v[22:25], off sc1
	v_or_b32_e32 v4, s4, v50
	v_lshlrev_b32_e32 v4, 13, v4
	s_waitcnt lgkmcnt(0)
	v_cvt_pk_bf16_f32 v22, v26, v27
	ds_read2_b32 v[24:25], v47 offset0:90 offset1:123
	s_waitcnt lgkmcnt(0)
	v_cvt_pk_bf16_f32 v23, v24, v25
	ds_read2_b32 v[24:25], v47 offset0:156 offset1:189
	s_waitcnt lgkmcnt(0)
	v_cvt_pk_bf16_f32 v24, v24, v25
	ds_read2_b32 v[26:27], v47 offset0:222 offset1:255
	s_waitcnt lgkmcnt(0)
	v_cvt_pk_bf16_f32 v25, v26, v27
	v_lshl_add_u64 v[26:27], v[28:29], 0, v[4:5]
	global_store_dwordx4 v[26:27], v[22:25], off sc1
	s_waitcnt lgkmcnt(0)
